# v37: v35 + MLA small trims (hoisted LDS store address parts, dropped canonicalising max/add-zero)
# baseline (speedup 1.0000x reference)
.Lmla_prio_done:
	v_and_b32_e32 v4, 31, v146
	v_lshrrev_b32_e32 v0, 1, v146
	s_movk_i32 s2, 0x1e0
	v_and_or_b32 v153, v0, s2, v4
	v_add_u32_e32 v5, 0x200, v146
	s_movk_i32 s2, 0x100
	v_cmp_gt_u32_e64 s[10:11], s2, v146
	v_mul_u32_u24_e32 v7, 0x1556, v146
	v_mul_u32_u24_e32 v9, 0x1556, v5
	s_mov_b32 s2, 0x7060302
	v_lshrrev_b32_e32 v8, 16, v7
	v_lshrrev_b32_e32 v10, 16, v9
	v_perm_b32 v7, v9, v7, s2
	s_movk_i32 s4, 0x68
	v_mad_i32_i24 v5, v10, -12, v5
	v_pk_mul_lo_u16 v7, v7, s4 op_sel_hi:[1,0]
	v_bfe_u32 v1, v146, 5, 1
	v_and_b32_e32 v6, 56, v147
	v_lshlrev_b32_e32 v142, 3, v5
	v_lshrrev_b32_e32 v180, 16, v7
	v_lshlrev_b32_e32 v5, 4, v5
	v_lshlrev_b32_e32 v0, 3, v1
	v_lshl_add_u32 v181, v180, 1, v5
	v_lshlrev_b32_e32 v158, 1, v6
	v_mul_u32_u24_e32 v5, 0x68, v4
	v_lshlrev_b32_e32 v6, 4, v1
	v_lshlrev_b32_e32 v253, 2, v1
	v_mbcnt_hi_u32_b32 v1, -1, v145
	v_lshl_add_u32 v184, v5, 1, v6
	v_and_b32_e32 v5, 64, v1
	v_mov_b32_e32 v97, 0
	v_mul_u32_u24_e32 v96, 0x4200, v154
	v_mad_i32_i24 v9, v8, -12, v146
	v_mul_u32_u24_e32 v185, 0x48, v4
	v_xor_b32_e32 v4, 32, v1
	v_add_u32_e32 v5, 64, v5
	v_lshl_add_u64 v[2:3], s[12:13], 0, v[96:97]
	v_lshlrev_b32_e32 v138, 3, v9
	v_ashrrev_i32_e32 v143, 31, v142
	v_cmp_lt_i32_e32 vcc, v4, v5
	v_mov_b32_e32 v159, v97
	s_movk_i32 s2, 0xc00
	v_ashrrev_i32_e32 v139, 31, v138
	v_cndmask_b32_e32 v1, v1, v4, vcc
	v_lshl_add_u64 v[162:163], v[2:3], 0, v[158:159]
	v_lshlrev_b64 v[2:3], 1, v[142:143]
	v_and_b32_e32 v11, 0xfff8, v7
	v_lshlrev_b32_e32 v9, 4, v9
	v_mul_u32_u24_e32 v182, 0x48, v154
	v_lshlrev_b32_e32 v186, 2, v1
	v_and_b32_e32 v1, 7, v146
	v_mad_u64_u32 v[166:167], s[4:5], v10, s2, v[2:3]
	v_lshlrev_b64 v[2:3], 1, v[138:139]
	v_mul_hi_u32_u24_e32 v137, 0xc00, v8
	v_mul_u32_u24_e32 v136, 0xc00, v8
	v_mul_u32_u24_e32 v140, 0xc00, v10
	v_mov_b32_e32 v141, v97
	v_lshl_add_u32 v161, v11, 1, v9
	v_lshl_add_u32 v183, v182, 1, v158
	s_mov_b32 s39, 0
	v_lshl_or_b32 v159, v185, 1, v0
	v_lshl_or_b32 v164, v1, 4, v96
	v_mov_b32_e32 v165, v97
	v_mad_u64_u32 v[168:169], s[4:5], v8, s2, v[2:3]
	v_mov_b32_e32 v187, 0x2100
	v_mov_b64_e32 v[170:171], s[94:95]
	v_lshlrev_b32_e32 v172, 1, v0
	v_mov_b32_e32 v173, v97
	v_mov_b32_e32 v188, 0x108000
	v_mov_b32_e32 v189, 0xc0
	s_mov_b64 s[40:41], 0x100
	s_mov_b64 s[42:43], 0x60000
	v_lshlrev_b32_e32 v190, 1, v11
	s_mov_b32 s6, s3
	v_mov_b32_e32 v252, 0x12000
	v_lshl_add_u32 v252, v146, 6, v252
	v_add_u32_e32 v177, v180, v142
	v_lshlrev_b32_e32 v177, 1, v177
	v_lshl_add_u32 v179, v138, 1, v190
	s_branch .LBB0_2694

.LBB0_2710:
	s_add_i32 s18, s16, -2
	s_cmp_lt_u32 s18, s8
	s_mov_b32 s17, s4
	s_cselect_b64 s[14:15], -1, 0
	s_cmp_ge_u32 s18, s8
	s_mul_i32 s19, s4, 0x3400
	s_barrier
	s_cbranch_scc1 .LBB0_2717
	v_add_u32_e32 v64, s19, v179
	s_waitcnt vmcnt(1)
	ds_write_b128 v64, v[128:131]
	s_and_saveexec_b64 s[4:5], s[10:11]
	v_add_u32_e32 v64, s19, v177
	ds_write_b128 v64, v[124:127]
	s_or_b64 exec, exec, s[4:5]
	s_mul_i32 s4, s17, 0x2400
	v_add_u32_e32 v64, s4, v183
	s_add_i32 s4, s16, -1
	s_cmp_ge_u32 s4, s8
	s_waitcnt vmcnt(0)
	ds_write_b128 v64, v[132:135] offset:39936
	s_cbranch_scc1 .LBB0_2717
	global_load_dwordx4 v[128:131], v178, s[98:99]
	s_and_saveexec_b64 s[4:5], s[10:11]
	s_cbranch_execz .LBB0_2716
	global_load_dwordx4 v[124:127], v176, s[98:99]

.LBB0_2717:
	s_mul_i32 s4, s13, 0x3400
	v_add_u32_e32 v227, s4, v184
	ds_read_b128 v[236:239], v227
	ds_read_b128 v[240:243], v227 offset:32
	ds_read_b128 v[244:247], v227 offset:64
	ds_read_b128 v[248:251], v227 offset:96
	ds_read_b128 v[228:231], v227 offset:128
	ds_read_b128 v[232:235], v227 offset:160
	v_max_f32_e32 v96, v48, v49
	v_max3_f32 v96, v96, v50, v51
	v_max3_f32 v96, v96, v52, v53
	v_max3_f32 v96, v96, v54, v55
	s_waitcnt lgkmcnt(5)
	v_mfma_f32_32x32x16_bf16 v[80:95], v[236:239], v[100:103], v[160:175]
	ds_read_b128 v[236:239], v227 offset:6656
	v_max3_f32 v96, v96, v56, v57
	v_max3_f32 v96, v96, v58, v59
	v_max3_f32 v96, v96, v60, v61
	v_max3_f32 v96, v96, v62, v63
	s_waitcnt lgkmcnt(5)
	v_mfma_f32_32x32x16_bf16 v[80:95], v[240:243], v[104:107], v[80:95]
	ds_read_b128 v[240:243], v227 offset:6688
	v_max3_f32 v96, v96, v32, v33
	v_max3_f32 v96, v96, v34, v35
	v_max3_f32 v96, v96, v36, v37
	v_max3_f32 v96, v96, v38, v39
	s_waitcnt lgkmcnt(5)
	v_mfma_f32_32x32x16_bf16 v[80:95], v[244:247], v[108:111], v[80:95]
	ds_read_b128 v[244:247], v227 offset:6720
	v_max3_f32 v96, v96, v40, v41
	v_max3_f32 v96, v96, v42, v43
	v_max3_f32 v96, v96, v44, v45
	v_max3_f32 v96, v96, v46, v47
	v_cmp_lt_f32_e32 vcc, 0x41000000, v96
	s_waitcnt lgkmcnt(5)
	v_mfma_f32_32x32x16_bf16 v[80:95], v[248:251], v[112:115], v[80:95]
	ds_read_b128 v[248:251], v227 offset:6752
	s_cbranch_vccz .LBB0_2719
	ds_bpermute_b32 v193, v186, v96
	s_waitcnt lgkmcnt(0)
	v_max_f32_e32 v193, v96, v193
	v_max_f32_e32 v193, 0, v193
	v_sub_f32_e32 v96, 0, v193
	v_exp_f32_e32 v96, v96
	s_nop 0
	v_mul_f32_e32 v192, v192, v96
	v_pk_mul_f32 v[30:31], v[30:31], v[96:97] op_sel_hi:[1,0]
	v_pk_mul_f32 v[28:29], v[28:29], v[96:97] op_sel_hi:[1,0]
	v_pk_mul_f32 v[26:27], v[26:27], v[96:97] op_sel_hi:[1,0]
	v_pk_mul_f32 v[24:25], v[24:25], v[96:97] op_sel_hi:[1,0]
	v_pk_mul_f32 v[22:23], v[22:23], v[96:97] op_sel_hi:[1,0]
	v_pk_mul_f32 v[20:21], v[20:21], v[96:97] op_sel_hi:[1,0]
	v_pk_mul_f32 v[18:19], v[18:19], v[96:97] op_sel_hi:[1,0]
	v_pk_mul_f32 v[16:17], v[16:17], v[96:97] op_sel_hi:[1,0]
	v_pk_mul_f32 v[14:15], v[14:15], v[96:97] op_sel_hi:[1,0]
	v_pk_mul_f32 v[12:13], v[12:13], v[96:97] op_sel_hi:[1,0]
	v_pk_mul_f32 v[10:11], v[10:11], v[96:97] op_sel_hi:[1,0]
	v_pk_mul_f32 v[8:9], v[8:9], v[96:97] op_sel_hi:[1,0]
	v_pk_mul_f32 v[6:7], v[6:7], v[96:97] op_sel_hi:[1,0]
	v_pk_mul_f32 v[4:5], v[4:5], v[96:97] op_sel_hi:[1,0]
	v_pk_mul_f32 v[2:3], v[2:3], v[96:97] op_sel_hi:[1,0]
	v_pk_mul_f32 v[0:1], v[0:1], v[96:97] op_sel_hi:[1,0]
	v_sub_f32_e32 v160, v160, v193
	v_sub_f32_e32 v161, v161, v193
	v_sub_f32_e32 v162, v162, v193
	v_sub_f32_e32 v163, v163, v193
	v_sub_f32_e32 v164, v164, v193
	v_sub_f32_e32 v165, v165, v193
	v_sub_f32_e32 v166, v166, v193
	v_sub_f32_e32 v167, v167, v193
	v_sub_f32_e32 v168, v168, v193
	v_sub_f32_e32 v169, v169, v193
	v_sub_f32_e32 v170, v170, v193
	v_sub_f32_e32 v171, v171, v193
	v_sub_f32_e32 v172, v172, v193
	v_sub_f32_e32 v173, v173, v193
	v_sub_f32_e32 v174, v174, v193
	v_sub_f32_e32 v175, v175, v193
	v_sub_f32_e32 v48, v48, v193
	v_sub_f32_e32 v49, v49, v193
	v_sub_f32_e32 v50, v50, v193
	v_sub_f32_e32 v51, v51, v193
	v_sub_f32_e32 v52, v52, v193
	v_sub_f32_e32 v53, v53, v193
	v_sub_f32_e32 v54, v54, v193
	v_sub_f32_e32 v55, v55, v193
	v_sub_f32_e32 v56, v56, v193
	v_sub_f32_e32 v57, v57, v193
	v_sub_f32_e32 v58, v58, v193
	v_sub_f32_e32 v59, v59, v193
	v_sub_f32_e32 v60, v60, v193
	v_sub_f32_e32 v61, v61, v193
	v_sub_f32_e32 v62, v62, v193
	v_sub_f32_e32 v63, v63, v193
	v_sub_f32_e32 v32, v32, v193
	v_sub_f32_e32 v33, v33, v193
	v_sub_f32_e32 v34, v34, v193
	v_sub_f32_e32 v35, v35, v193
	v_sub_f32_e32 v36, v36, v193
	v_sub_f32_e32 v37, v37, v193
	v_sub_f32_e32 v38, v38, v193
	v_sub_f32_e32 v39, v39, v193
	v_sub_f32_e32 v40, v40, v193
	v_sub_f32_e32 v41, v41, v193
	v_sub_f32_e32 v42, v42, v193
	v_sub_f32_e32 v43, v43, v193
	v_sub_f32_e32 v44, v44, v193
	v_sub_f32_e32 v45, v45, v193
	v_sub_f32_e32 v46, v46, v193
	v_sub_f32_e32 v47, v47, v193
	v_sub_f32_e32 v80, v80, v193
	v_sub_f32_e32 v81, v81, v193
	v_sub_f32_e32 v82, v82, v193
	v_sub_f32_e32 v83, v83, v193
	v_sub_f32_e32 v84, v84, v193
	v_sub_f32_e32 v85, v85, v193
	v_sub_f32_e32 v86, v86, v193
	v_sub_f32_e32 v87, v87, v193
	v_sub_f32_e32 v88, v88, v193
	v_sub_f32_e32 v89, v89, v193
	v_sub_f32_e32 v90, v90, v193
	v_sub_f32_e32 v91, v91, v193
	v_sub_f32_e32 v92, v92, v193
	v_sub_f32_e32 v93, v93, v193
	v_sub_f32_e32 v94, v94, v193
	v_sub_f32_e32 v95, v95, v193
.LBB0_2719:
	v_exp_f32_e32 v193, v48
	v_exp_f32_e32 v195, v49
	s_waitcnt lgkmcnt(5)
	v_mfma_f32_32x32x16_bf16 v[80:95], v[228:231], v[116:119], v[80:95]
	ds_read_b128 v[228:231], v227 offset:6784
	v_exp_f32_e32 v196, v50
	v_exp_f32_e32 v197, v51
	s_waitcnt lgkmcnt(5)
	v_mfma_f32_32x32x16_bf16 v[80:95], v[232:235], v[120:123], v[80:95]
	ds_read_b128 v[232:235], v227 offset:6816
	v_exp_f32_e32 v199, v52
	v_exp_f32_e32 v200, v53
	s_waitcnt lgkmcnt(5)
	v_mfma_f32_32x32x16_bf16 v[64:79], v[236:239], v[100:103], v[160:175]
	v_exp_f32_e32 v201, v54
	v_exp_f32_e32 v202, v55
	s_waitcnt lgkmcnt(4)
	v_mfma_f32_32x32x16_bf16 v[64:79], v[240:243], v[104:107], v[64:79]
	v_exp_f32_e32 v203, v56
	v_exp_f32_e32 v204, v57
	s_waitcnt lgkmcnt(3)
	v_mfma_f32_32x32x16_bf16 v[64:79], v[244:247], v[108:111], v[64:79]
	v_exp_f32_e32 v205, v58
	s_waitcnt lgkmcnt(2)
	v_mfma_f32_32x32x16_bf16 v[64:79], v[248:251], v[112:115], v[64:79]
	s_mul_i32 s20, s12, 0x2400
	v_exp_f32_e32 v206, v59
	v_exp_f32_e32 v211, v32
	v_mov_b32_e32 v32, v33
	s_waitcnt lgkmcnt(1)
	v_mfma_f32_32x32x16_bf16 v[64:79], v[228:231], v[116:119], v[64:79]
	v_lshlrev_b32_e32 v33, 1, v185
	v_lshlrev_b32_e32 v96, 1, v253
	v_exp_f32_e32 v207, v60
	s_waitcnt lgkmcnt(0)
	v_mfma_f32_32x32x16_bf16 v[64:79], v[232:235], v[120:123], v[64:79]
	v_add3_u32 v52, s20, v33, v96
	v_exp_f32_e32 v208, v61
	v_add_u32_e32 v58, 0xa800, v52
	v_exp_f32_e32 v209, v62
	v_add_u32_e32 v56, 0x9800, v52
	ds_read_b64 v[52:53], v58 offset:1536
	ds_read_b64 v[54:55], v58 offset:1552
	v_exp_f32_e32 v210, v63
	ds_read_b64 v[48:49], v56 offset:1024
	ds_read_b64 v[50:51], v56 offset:1040
	v_exp_f32_e32 v212, v32
	v_exp_f32_e32 v215, v36
	v_exp_f32_e32 v213, v34
	v_mov_b32_e32 v57, v35
	v_cvt_pk_bf16_f32 v32, v193, v195
	v_cvt_pk_bf16_f32 v33, v196, v197
	v_cvt_pk_bf16_f32 v34, v199, v200
	v_cvt_pk_bf16_f32 v35, v201, v202
	v_exp_f32_e32 v216, v37
	s_waitcnt lgkmcnt(2)
	v_mfma_f32_32x32x16_bf16 v[0:15], v[52:55], v[32:35], v[0:15]
	v_exp_f32_e32 v217, v38
	v_mov_b32_e32 v52, v39
	ds_read_b64 v[36:37], v58 offset:1568
	ds_read_b64 v[38:39], v58 offset:1584
	v_exp_f32_e32 v214, v57
	v_exp_f32_e32 v218, v52
	v_exp_f32_e32 v219, v40
	s_waitcnt lgkmcnt(2)
	v_mfma_f32_32x32x16_bf16 v[16:31], v[48:51], v[32:35], v[16:31]
	ds_read_b64 v[48:49], v56 offset:1056
	ds_read_b64 v[50:51], v56 offset:1072
	v_cvt_pk_bf16_f32 v32, v203, v204
	v_cvt_pk_bf16_f32 v33, v205, v206
	v_cvt_pk_bf16_f32 v34, v207, v208
	v_cvt_pk_bf16_f32 v35, v209, v210
	v_exp_f32_e32 v220, v41
	s_waitcnt lgkmcnt(2)
	v_mfma_f32_32x32x16_bf16 v[0:15], v[36:39], v[32:35], v[0:15]
	ds_read_b64 v[36:37], v58 offset:1600
	ds_read_b64 v[38:39], v58 offset:1616
	v_exp_f32_e32 v221, v42
	v_exp_f32_e32 v222, v43
	v_exp_f32_e32 v223, v44
	s_waitcnt lgkmcnt(2)
	v_mfma_f32_32x32x16_bf16 v[16:31], v[48:51], v[32:35], v[16:31]
	ds_read_b64 v[48:49], v56 offset:1088
	ds_read_b64 v[50:51], v56 offset:1104
	v_cvt_pk_bf16_f32 v32, v211, v212
	v_cvt_pk_bf16_f32 v33, v213, v214
	v_cvt_pk_bf16_f32 v34, v215, v216
	v_cvt_pk_bf16_f32 v35, v217, v218
	v_exp_f32_e32 v224, v45
	ds_read_b64 v[40:41], v56 offset:1120
	ds_read_b64 v[42:43], v56 offset:1136
	s_waitcnt lgkmcnt(4)
	v_mfma_f32_32x32x16_bf16 v[0:15], v[36:39], v[32:35], v[0:15]
	ds_read_b64 v[36:37], v58 offset:1632
	ds_read_b64 v[38:39], v58 offset:1648
	v_exp_f32_e32 v225, v46
	s_add_i32 s4, s16, -4
	s_cmp_ge_u32 s4, s9
	s_waitcnt lgkmcnt(0)
	s_barrier
	v_mfma_f32_32x32x16_bf16 v[16:31], v[48:51], v[32:35], v[16:31]
	v_exp_f32_e32 v226, v47
	v_cvt_pk_bf16_f32 v32, v219, v220
	v_cvt_pk_bf16_f32 v33, v221, v222
	v_cvt_pk_bf16_f32 v34, v223, v224
	v_cvt_pk_bf16_f32 v35, v225, v226
	s_nop 1
	v_mfma_f32_32x32x16_bf16 v[16:31], v[40:43], v[32:35], v[16:31]
	v_mfma_f32_32x32x16_bf16 v[0:15], v[36:39], v[32:35], v[0:15]
	s_cbranch_scc1 .LBB0_2726
	s_mul_i32 s21, s12, 0x3400
	v_add_u32_e32 v32, s21, v179
	s_waitcnt vmcnt(1)
	ds_write_b128 v32, v[128:131]
	s_and_saveexec_b64 s[4:5], s[10:11]
	v_add_u32_e32 v32, s21, v177
	ds_write_b128 v32, v[124:127]
	s_or_b64 exec, exec, s[4:5]
	v_lshlrev_b32_e32 v32, 1, v182
	v_add3_u32 v32, s20, v32, v158
	s_cmp_ge_u32 s16, s8
	s_waitcnt vmcnt(0)
	ds_write_b128 v32, v[132:135] offset:39936
	s_cbranch_scc1 .LBB0_2726
	global_load_dwordx4 v[128:131], v178, s[98:99]
	s_and_saveexec_b64 s[4:5], s[10:11]
	s_cbranch_execz .LBB0_2725
	global_load_dwordx4 v[124:127], v176, s[98:99]

.LBB0_2728:
	v_add_f32_e32 v193, v196, v193
	v_add_f32_e32 v195, v197, v195
	s_waitcnt lgkmcnt(5)
	v_mfma_f32_32x32x16_bf16 v[48:63], v[236:239], v[100:103], v[160:175]
	ds_read_b128 v[236:239], v198 offset:6656
	v_add_f32_e32 v193, v199, v193
	v_add_f32_e32 v195, v200, v195
	v_add_f32_e32 v193, v201, v193
	v_add_f32_e32 v195, v202, v195
	s_waitcnt lgkmcnt(5)
	v_mfma_f32_32x32x16_bf16 v[48:63], v[240:243], v[104:107], v[48:63]
	ds_read_b128 v[240:243], v198 offset:6688
	v_add_f32_e32 v193, v203, v193
	v_add_f32_e32 v195, v204, v195
	v_add_f32_e32 v193, v205, v193
	v_add_f32_e32 v195, v206, v195
	s_waitcnt lgkmcnt(5)
	v_mfma_f32_32x32x16_bf16 v[48:63], v[244:247], v[108:111], v[48:63]
	ds_read_b128 v[244:247], v198 offset:6720
	v_add_f32_e32 v193, v207, v193
	v_add_f32_e32 v195, v208, v195
	v_add_f32_e32 v193, v209, v193
	v_add_f32_e32 v195, v210, v195
	s_waitcnt lgkmcnt(5)
	v_mfma_f32_32x32x16_bf16 v[48:63], v[248:251], v[112:115], v[48:63]
	ds_read_b128 v[248:251], v198 offset:6752
	v_add_f32_e32 v193, v211, v193
	v_add_f32_e32 v195, v212, v195
	v_add_f32_e32 v193, v213, v193
	v_add_f32_e32 v195, v214, v195
	s_waitcnt lgkmcnt(5)
	v_mfma_f32_32x32x16_bf16 v[48:63], v[228:231], v[116:119], v[48:63]
	ds_read_b128 v[228:231], v198 offset:6784
	v_add_f32_e32 v193, v215, v193
	v_add_f32_e32 v195, v216, v195
	v_add_f32_e32 v193, v217, v193
	v_add_f32_e32 v195, v218, v195
	s_waitcnt lgkmcnt(5)
	v_mfma_f32_32x32x16_bf16 v[48:63], v[232:235], v[120:123], v[48:63]
	ds_read_b128 v[232:235], v198 offset:6816
	v_add_f32_e32 v193, v219, v193
	v_add_f32_e32 v195, v220, v195
	v_add_f32_e32 v193, v221, v193
	v_add_f32_e32 v195, v222, v195
	s_waitcnt lgkmcnt(5)
	v_mfma_f32_32x32x16_bf16 v[32:47], v[236:239], v[100:103], v[160:175]
	v_add_f32_e32 v193, v223, v193
	v_add_f32_e32 v195, v224, v195
	v_add_f32_e32 v193, v225, v193
	v_add_f32_e32 v195, v226, v195
	s_waitcnt lgkmcnt(4)
	v_mfma_f32_32x32x16_bf16 v[32:47], v[240:243], v[104:107], v[32:47]
	v_add_f32_e32 v193, v195, v193
	v_add_f32_e32 v192, v192, v193
	s_waitcnt lgkmcnt(3)
	v_mfma_f32_32x32x16_bf16 v[32:47], v[244:247], v[108:111], v[32:47]
	v_max_f32_e32 v193, v80, v81
	v_max3_f32 v193, v193, v82, v83
	v_max3_f32 v193, v193, v84, v85
	v_max3_f32 v193, v193, v86, v87
	s_waitcnt lgkmcnt(2)
	v_mfma_f32_32x32x16_bf16 v[32:47], v[248:251], v[112:115], v[32:47]
	v_max3_f32 v193, v193, v88, v89
	v_max3_f32 v193, v193, v90, v91
	v_max3_f32 v193, v193, v92, v93
	v_max3_f32 v193, v193, v94, v95
	s_waitcnt lgkmcnt(1)
	v_mfma_f32_32x32x16_bf16 v[32:47], v[228:231], v[116:119], v[32:47]
	v_max3_f32 v193, v193, v64, v65
	v_max3_f32 v193, v193, v66, v67
	v_max3_f32 v193, v193, v68, v69
	v_max3_f32 v193, v193, v70, v71
	s_waitcnt lgkmcnt(0)
	v_mfma_f32_32x32x16_bf16 v[32:47], v[232:235], v[120:123], v[32:47]
	v_max3_f32 v193, v193, v72, v73
	v_max3_f32 v193, v193, v74, v75
	v_max3_f32 v193, v193, v76, v77
	v_max3_f32 v193, v193, v78, v79
	v_cmp_lt_f32_e32 vcc, 0x41000000, v193
	s_cbranch_vccz .LBB0_2730
	ds_bpermute_b32 v195, v186, v193
	s_waitcnt lgkmcnt(0)
	v_max_f32_e32 v195, v193, v195
	v_max_f32_e32 v195, 0, v195
	v_sub_f32_e32 v196, 0, v195
	v_exp_f32_e32 v196, v196
	s_nop 0
	v_mul_f32_e32 v192, v192, v196
	v_pk_mul_f32 v[30:31], v[30:31], v[196:197] op_sel_hi:[1,0]
	v_pk_mul_f32 v[28:29], v[28:29], v[196:197] op_sel_hi:[1,0]
	v_pk_mul_f32 v[26:27], v[26:27], v[196:197] op_sel_hi:[1,0]
	v_pk_mul_f32 v[24:25], v[24:25], v[196:197] op_sel_hi:[1,0]
	v_pk_mul_f32 v[22:23], v[22:23], v[196:197] op_sel_hi:[1,0]
	v_pk_mul_f32 v[20:21], v[20:21], v[196:197] op_sel_hi:[1,0]
	v_pk_mul_f32 v[18:19], v[18:19], v[196:197] op_sel_hi:[1,0]
	v_pk_mul_f32 v[16:17], v[16:17], v[196:197] op_sel_hi:[1,0]
	v_pk_mul_f32 v[14:15], v[14:15], v[196:197] op_sel_hi:[1,0]
	v_pk_mul_f32 v[12:13], v[12:13], v[196:197] op_sel_hi:[1,0]
	v_pk_mul_f32 v[10:11], v[10:11], v[196:197] op_sel_hi:[1,0]
	v_pk_mul_f32 v[8:9], v[8:9], v[196:197] op_sel_hi:[1,0]
	v_pk_mul_f32 v[6:7], v[6:7], v[196:197] op_sel_hi:[1,0]
	v_pk_mul_f32 v[4:5], v[4:5], v[196:197] op_sel_hi:[1,0]
	v_pk_mul_f32 v[2:3], v[2:3], v[196:197] op_sel_hi:[1,0]
	v_pk_mul_f32 v[0:1], v[0:1], v[196:197] op_sel_hi:[1,0]
	v_sub_f32_e32 v160, v160, v195
	v_sub_f32_e32 v161, v161, v195
	v_sub_f32_e32 v162, v162, v195
	v_sub_f32_e32 v163, v163, v195
	v_sub_f32_e32 v164, v164, v195
	v_sub_f32_e32 v165, v165, v195
	v_sub_f32_e32 v166, v166, v195
	v_sub_f32_e32 v167, v167, v195
	v_sub_f32_e32 v168, v168, v195
	v_sub_f32_e32 v169, v169, v195
	v_sub_f32_e32 v170, v170, v195
	v_sub_f32_e32 v171, v171, v195
	v_sub_f32_e32 v172, v172, v195
	v_sub_f32_e32 v173, v173, v195
	v_sub_f32_e32 v174, v174, v195
	v_sub_f32_e32 v175, v175, v195
	v_sub_f32_e32 v80, v80, v195
	v_sub_f32_e32 v81, v81, v195
	v_sub_f32_e32 v82, v82, v195
	v_sub_f32_e32 v83, v83, v195
	v_sub_f32_e32 v84, v84, v195
	v_sub_f32_e32 v85, v85, v195
	v_sub_f32_e32 v86, v86, v195
	v_sub_f32_e32 v87, v87, v195
	v_sub_f32_e32 v88, v88, v195
	v_sub_f32_e32 v89, v89, v195
	v_sub_f32_e32 v90, v90, v195
	v_sub_f32_e32 v91, v91, v195
	v_sub_f32_e32 v92, v92, v195
	v_sub_f32_e32 v93, v93, v195
	v_sub_f32_e32 v94, v94, v195
	v_sub_f32_e32 v95, v95, v195
	v_sub_f32_e32 v64, v64, v195
	v_sub_f32_e32 v65, v65, v195
	v_sub_f32_e32 v66, v66, v195
	v_sub_f32_e32 v67, v67, v195
	v_sub_f32_e32 v68, v68, v195
	v_sub_f32_e32 v69, v69, v195
	v_sub_f32_e32 v70, v70, v195
	v_sub_f32_e32 v71, v71, v195
	v_sub_f32_e32 v72, v72, v195
	v_sub_f32_e32 v73, v73, v195
	v_sub_f32_e32 v74, v74, v195
	v_sub_f32_e32 v75, v75, v195
	v_sub_f32_e32 v76, v76, v195
	v_sub_f32_e32 v77, v77, v195
	v_sub_f32_e32 v78, v78, v195
	v_sub_f32_e32 v79, v79, v195
	v_sub_f32_e32 v48, v48, v195
	v_sub_f32_e32 v49, v49, v195
	v_sub_f32_e32 v50, v50, v195
	v_sub_f32_e32 v51, v51, v195
	v_sub_f32_e32 v52, v52, v195
	v_sub_f32_e32 v53, v53, v195
	v_sub_f32_e32 v54, v54, v195
	v_sub_f32_e32 v55, v55, v195
	v_sub_f32_e32 v56, v56, v195
	v_sub_f32_e32 v57, v57, v195
	v_sub_f32_e32 v58, v58, v195
	v_sub_f32_e32 v59, v59, v195
	v_sub_f32_e32 v60, v60, v195
	v_sub_f32_e32 v61, v61, v195
	v_sub_f32_e32 v62, v62, v195
	v_sub_f32_e32 v63, v63, v195
	v_sub_f32_e32 v32, v32, v195
	v_sub_f32_e32 v33, v33, v195
	v_sub_f32_e32 v34, v34, v195
	v_sub_f32_e32 v35, v35, v195
	v_sub_f32_e32 v36, v36, v195
	v_sub_f32_e32 v37, v37, v195
	v_sub_f32_e32 v38, v38, v195
	v_sub_f32_e32 v39, v39, v195
	v_sub_f32_e32 v40, v40, v195
	v_sub_f32_e32 v41, v41, v195
	v_sub_f32_e32 v42, v42, v195
	v_sub_f32_e32 v43, v43, v195
	v_sub_f32_e32 v44, v44, v195
	v_sub_f32_e32 v45, v45, v195
	v_sub_f32_e32 v46, v46, v195
	v_sub_f32_e32 v47, v47, v195
